# gemm_out: residual and gate operand loads of a tile issued after its last DMA (start of the k-loop tail) instead of before the first, so the first k-steps no longer wait behind them; tail waits recoun
# speedup vs baseline: 1.0432x; 1.0010x over previous
.LBB0_1352:
	s_lshr_b32 s4, s0, 4
	s_and_b32 s4, s4, 0x78
	s_and_b32 s5, s0, 7
	s_lshl_b32 s0, s0, 4
	s_or_b32 s4, s4, s5
	s_and_b32 s7, s0, 0x780
	s_lshl_b32 s4, s4, 7
	v_readfirstlane_b32 s8, v128
	v_readfirstlane_b32 s9, v129
	v_readfirstlane_b32 s10, v130
	v_readfirstlane_b32 s11, v131
	v_lshrrev_b32_e32 v198, 6, v171
	v_and_b32_e32 v199, 63, v171
	v_readfirstlane_b32 s12, v198
	s_lshl_b32 s16, s7, 12
	s_add_u32 s8, s8, s16
	s_addc_u32 s9, s9, 0
	s_lshl_b32 s16, s4, 12
	s_add_u32 s10, s10, s16
	s_addc_u32 s11, s11, 0
	s_add_u32 s14, s10, 0x20000
	s_addc_u32 s15, s11, 0
	v_lshrrev_b32_e32 v194, 4, v199
	v_and_b32_e32 v190, 7, v199
	v_lshrrev_b32_e32 v191, 3, v199
	s_and_b32 s16, s12, 1
	s_lshl_b32 s16, s16, 2
	v_or_b32_e32 v196, s16, v194
	v_xor_b32_e32 v190, v190, v196
	v_lshlrev_b32_e32 v190, 4, v190
	v_lshl_or_b32 v190, v191, 12, v190
	s_lshl_b32 s16, s12, 15
	v_add_u32_e32 v190, s16, v190
	v_add_u32_e32 v191, 0x20000, v190
	v_add_u32_e32 v192, 0x40000, v190
	v_add_u32_e32 v193, 0x60000, v190
	v_and_b32_e32 v198, 15, v199
	v_bfe_u32 v196, v198, 1, 3
	v_xor_b32_e32 v196, v196, v194
	v_lshlrev_b32_e32 v196, 4, v196
	v_lshl_or_b32 v196, v198, 7, v196
	s_and_b32 s16, s12, 1
	s_lshl_b32 s16, s16, 13
	v_add_u32_e32 v194, s16, v196
	s_lshr_b32 s17, s12, 1
	s_lshl_b32 s17, s17, 12
	s_add_u32 s17, s17, 0x8000
	v_add_u32_e32 v196, s17, v196
	v_xor_b32_e32 v195, 64, v194
	v_xor_b32_e32 v197, 64, v196
	s_lshl_b32 s12, s12, 10
	s_barrier
	s_lshl_b32 s16, s4, 13
	s_lshl_b32 s17, s7, 2
	s_add_u32 s16, s16, s17
	s_add_u32 s18, s94, s16
	s_addc_u32 s19, s95, 0
	v_readlane_b32 s36, v253, 0
	v_readlane_b32 s37, v253, 1
	v_readlane_b32 s40, v253, 2
	v_readlane_b32 s41, v253, 3
	s_cmpk_lt_u32 s4, 0x2000
	s_cselect_b32 s36, s36, s40
	s_cselect_b32 s37, s37, s41
	s_cselect_b32 s40, 0, 0x4000000
	s_sub_u32 s41, s16, s40
	s_add_u32 s36, s36, s41
	s_addc_u32 s37, s37, 0
	s_cmp_lg_u32 s46, 0
	s_cselect_b32 s36, s18, s36
	s_cselect_b32 s37, s19, s37
	s_sub_u32 s40, s4, 0x2000
	s_lshr_b32 s40, s40, 10
	s_add_u32 s40, s40, 1
	s_cmpk_lt_u32 s4, 0x2000
	s_cselect_b32 s40, 0, s40
	s_add_u32 s40, s40, s48
	s_mul_i32 s40, s40, 0x6000
	s_add_u32 s40, s40, 0x4000
	s_add_u32 s40, s40, s17
	v_readlane_b32 s38, v254, 45
	v_readlane_b32 s39, v254, 46
	s_add_u32 s38, s38, s40
	s_addc_u32 s39, s39, 0
	v_and_b32_e32 v150, 15, v199
	v_lshrrev_b32_e32 v148, 4, v199
	s_lshr_b32 s40, s12, 11
	s_lshl_b32 s40, s40, 6
	v_add_u32_e32 v150, s40, v150
	s_bfe_u32 s41, s12, 0x1000a
	s_lshl_b32 s41, s41, 6
	v_lshl_add_u32 v148, v148, 2, s41
	v_lshlrev_b32_e32 v148, 2, v148
	v_lshl_add_u32 v150, v150, 13, v148
	v_add_u32_e32 v151, 0x20000, v150
	v_add_u32_e32 v152, 0x40000, v150
	v_add_u32_e32 v153, 0x60000, v150
	s_add_u32 m0, s12, 0x8000
	s_nop 0
	global_load_lds_dwordx4 v190, s[10:11]
	s_add_u32 m0, s12, 0x9000
	s_nop 0
	global_load_lds_dwordx4 v192, s[10:11]
	s_add_u32 s10, s10, 128
	s_addc_u32 s11, s11, 0
	s_add_u32 m0, s12, 0xa000
	s_nop 0
	global_load_lds_dwordx4 v190, s[14:15]
	s_add_u32 m0, s12, 0xb000
	s_nop 0
	global_load_lds_dwordx4 v192, s[14:15]
	s_add_u32 s14, s14, 128
	s_addc_u32 s15, s15, 0
	s_add_u32 m0, s12, 0x0
	s_nop 0
	global_load_lds_dwordx4 v190, s[8:9]
	s_add_u32 m0, s12, 0x1000
	s_nop 0
	global_load_lds_dwordx4 v191, s[8:9]
	s_add_u32 m0, s12, 0x2000
	s_nop 0
	global_load_lds_dwordx4 v192, s[8:9]
	s_add_u32 m0, s12, 0x3000
	s_nop 0
	global_load_lds_dwordx4 v193, s[8:9]
	s_add_u32 s8, s8, 128
	s_addc_u32 s9, s9, 0
	s_add_u32 m0, s12, 0xc000
	s_nop 0
	global_load_lds_dwordx4 v190, s[10:11]
	s_add_u32 m0, s12, 0xd000
	s_nop 0
	global_load_lds_dwordx4 v192, s[10:11]
	s_add_u32 s10, s10, 128
	s_addc_u32 s11, s11, 0
	s_add_u32 m0, s12, 0xe000
	s_nop 0
	global_load_lds_dwordx4 v190, s[14:15]
	s_add_u32 m0, s12, 0xf000
	s_nop 0
	global_load_lds_dwordx4 v192, s[14:15]
	s_add_u32 s14, s14, 128
	s_addc_u32 s15, s15, 0
	s_add_u32 m0, s12, 0x4000
	s_nop 0
	global_load_lds_dwordx4 v190, s[8:9]
	s_add_u32 m0, s12, 0x5000
	s_nop 0
	global_load_lds_dwordx4 v191, s[8:9]
	s_add_u32 m0, s12, 0x6000
	s_nop 0
	global_load_lds_dwordx4 v192, s[8:9]
	s_add_u32 m0, s12, 0x7000
	s_nop 0
	global_load_lds_dwordx4 v193, s[8:9]
	s_add_u32 s8, s8, 128
	s_addc_u32 s9, s9, 0
	v_mov_b32_e32 v0, 0
	v_mov_b32_e32 v1, v0
	v_mov_b32_e32 v2, v0
	v_mov_b32_e32 v3, v0
	v_mov_b32_e32 v4, v0
	v_mov_b32_e32 v5, v0
	v_mov_b32_e32 v6, v0
	v_mov_b32_e32 v7, v0
	v_mov_b32_e32 v8, v0
	v_mov_b32_e32 v9, v0
	v_mov_b32_e32 v10, v0
	v_mov_b32_e32 v11, v0
	v_mov_b32_e32 v12, v0
	v_mov_b32_e32 v13, v0
	v_mov_b32_e32 v14, v0
	v_mov_b32_e32 v15, v0
	v_mov_b32_e32 v16, v0
	v_mov_b32_e32 v17, v0
	v_mov_b32_e32 v18, v0
	v_mov_b32_e32 v19, v0
	v_mov_b32_e32 v20, v0
	v_mov_b32_e32 v21, v0
	v_mov_b32_e32 v22, v0
	v_mov_b32_e32 v23, v0
	v_mov_b32_e32 v24, v0
	v_mov_b32_e32 v25, v0
	v_mov_b32_e32 v26, v0
	v_mov_b32_e32 v27, v0
	v_mov_b32_e32 v28, v0
	v_mov_b32_e32 v29, v0
	v_mov_b32_e32 v30, v0
	v_mov_b32_e32 v31, v0
	v_mov_b32_e32 v32, v0
	v_mov_b32_e32 v33, v0
	v_mov_b32_e32 v34, v0
	v_mov_b32_e32 v35, v0
	v_mov_b32_e32 v36, v0
	v_mov_b32_e32 v37, v0
	v_mov_b32_e32 v38, v0
	v_mov_b32_e32 v39, v0
	v_mov_b32_e32 v40, v0
	v_mov_b32_e32 v41, v0
	v_mov_b32_e32 v42, v0
	v_mov_b32_e32 v43, v0
	v_mov_b32_e32 v44, v0
	v_mov_b32_e32 v45, v0
	v_mov_b32_e32 v46, v0
	v_mov_b32_e32 v47, v0
	v_mov_b32_e32 v48, v0
	v_mov_b32_e32 v49, v0
	v_mov_b32_e32 v50, v0
	v_mov_b32_e32 v51, v0
	v_mov_b32_e32 v52, v0
	v_mov_b32_e32 v53, v0
	v_mov_b32_e32 v54, v0
	v_mov_b32_e32 v55, v0
	v_mov_b32_e32 v56, v0
	v_mov_b32_e32 v57, v0
	v_mov_b32_e32 v58, v0
	v_mov_b32_e32 v59, v0
	v_mov_b32_e32 v124, v0
	v_mov_b32_e32 v125, v0
	v_mov_b32_e32 v126, v0
	v_mov_b32_e32 v127, v0
	s_mov_b32 s13, 0
.Lgout_loop:
	s_waitcnt vmcnt(8)
	s_barrier
	ds_read_b128 v[90:93], v194 offset:0
	ds_read_b128 v[94:97], v194 offset:2048
	ds_read_b128 v[98:101], v194 offset:4096
	ds_read_b128 v[102:105], v194 offset:6144
	ds_read_b128 v[132:135], v196 offset:0
	ds_read_b128 v[136:139], v196 offset:2048
	ds_read_b128 v[106:109], v195 offset:0
	ds_read_b128 v[110:113], v195 offset:2048
	ds_read_b128 v[114:117], v195 offset:4096
	ds_read_b128 v[118:121], v195 offset:6144
	ds_read_b128 v[140:143], v197 offset:0
	ds_read_b128 v[144:147], v197 offset:2048
	s_waitcnt lgkmcnt(7)
	s_add_u32 m0, s12, 0x10000
	v_mfma_f32_16x16x32_f16 v[124:127], v[90:93], v[132:135], v[124:127]
	global_load_lds_dwordx4 v190, s[10:11]
	v_mfma_f32_16x16x32_f16 v[44:47], v[94:97], v[132:135], v[44:47]
	v_mfma_f32_16x16x32_f16 v[28:31], v[98:101], v[132:135], v[28:31]
	v_mfma_f32_16x16x32_f16 v[12:15], v[102:105], v[132:135], v[12:15]
	s_waitcnt lgkmcnt(6)
	s_add_u32 m0, s12, 0x11000
	v_mfma_f32_16x16x32_f16 v[56:59], v[90:93], v[136:139], v[56:59]
	global_load_lds_dwordx4 v192, s[10:11]
	v_mfma_f32_16x16x32_f16 v[40:43], v[94:97], v[136:139], v[40:43]
	v_mfma_f32_16x16x32_f16 v[24:27], v[98:101], v[136:139], v[24:27]
	v_mfma_f32_16x16x32_f16 v[8:11], v[102:105], v[136:139], v[8:11]
	s_waitcnt lgkmcnt(1)
	v_mfma_f32_16x16x32_f16 v[124:127], v[106:109], v[140:143], v[124:127]
	v_mfma_f32_16x16x32_f16 v[44:47], v[110:113], v[140:143], v[44:47]
	v_mfma_f32_16x16x32_f16 v[28:31], v[114:117], v[140:143], v[28:31]
	v_mfma_f32_16x16x32_f16 v[12:15], v[118:121], v[140:143], v[12:15]
	s_waitcnt lgkmcnt(0)
	v_mfma_f32_16x16x32_f16 v[56:59], v[106:109], v[144:147], v[56:59]
	v_mfma_f32_16x16x32_f16 v[40:43], v[110:113], v[144:147], v[40:43]
	v_mfma_f32_16x16x32_f16 v[24:27], v[114:117], v[144:147], v[24:27]
	v_mfma_f32_16x16x32_f16 v[8:11], v[118:121], v[144:147], v[8:11]
	s_add_u32 s10, s10, 128
	s_addc_u32 s11, s11, 0
	s_barrier
	ds_read_b128 v[174:177], v196 offset:8192
	ds_read_b128 v[178:181], v196 offset:10240
	ds_read_b128 v[182:185], v197 offset:8192
	ds_read_b128 v[186:189], v197 offset:10240
	s_waitcnt lgkmcnt(3)
	s_add_u32 m0, s12, 0x8000
	v_mfma_f32_16x16x32_f16 v[52:55], v[90:93], v[174:177], v[52:55]
	global_load_lds_dwordx4 v190, s[14:15]
	v_mfma_f32_16x16x32_f16 v[36:39], v[94:97], v[174:177], v[36:39]
	s_add_u32 m0, s12, 0x9000
	v_mfma_f32_16x16x32_f16 v[20:23], v[98:101], v[174:177], v[20:23]
	global_load_lds_dwordx4 v192, s[14:15]
	v_mfma_f32_16x16x32_f16 v[4:7], v[102:105], v[174:177], v[4:7]
	s_waitcnt lgkmcnt(2)
	s_add_u32 m0, s12, 0x0
	v_mfma_f32_16x16x32_f16 v[48:51], v[90:93], v[178:181], v[48:51]
	global_load_lds_dwordx4 v190, s[8:9]
	v_mfma_f32_16x16x32_f16 v[32:35], v[94:97], v[178:181], v[32:35]
	s_add_u32 m0, s12, 0x1000
	v_mfma_f32_16x16x32_f16 v[16:19], v[98:101], v[178:181], v[16:19]
	global_load_lds_dwordx4 v191, s[8:9]
	v_mfma_f32_16x16x32_f16 v[0:3], v[102:105], v[178:181], v[0:3]
	s_waitcnt lgkmcnt(1)
	s_add_u32 m0, s12, 0x2000
	v_mfma_f32_16x16x32_f16 v[52:55], v[106:109], v[182:185], v[52:55]
	global_load_lds_dwordx4 v192, s[8:9]
	v_mfma_f32_16x16x32_f16 v[36:39], v[110:113], v[182:185], v[36:39]
	v_mfma_f32_16x16x32_f16 v[20:23], v[114:117], v[182:185], v[20:23]
	v_mfma_f32_16x16x32_f16 v[4:7], v[118:121], v[182:185], v[4:7]
	s_waitcnt lgkmcnt(0)
	s_add_u32 m0, s12, 0x3000
	v_mfma_f32_16x16x32_f16 v[48:51], v[106:109], v[186:189], v[48:51]
	global_load_lds_dwordx4 v193, s[8:9]
	v_mfma_f32_16x16x32_f16 v[32:35], v[110:113], v[186:189], v[32:35]
	v_mfma_f32_16x16x32_f16 v[16:19], v[114:117], v[186:189], v[16:19]
	v_mfma_f32_16x16x32_f16 v[0:3], v[118:121], v[186:189], v[0:3]
	s_add_u32 s14, s14, 128
	s_addc_u32 s15, s15, 0
	s_add_u32 s8, s8, 128
	s_addc_u32 s9, s9, 0
	s_waitcnt vmcnt(8)
	s_barrier
	ds_read_b128 v[90:93], v194 offset:16384
	ds_read_b128 v[94:97], v194 offset:18432
	ds_read_b128 v[98:101], v194 offset:20480
	ds_read_b128 v[102:105], v194 offset:22528
	ds_read_b128 v[132:135], v196 offset:16384
	ds_read_b128 v[136:139], v196 offset:18432
	ds_read_b128 v[106:109], v195 offset:16384
	ds_read_b128 v[110:113], v195 offset:18432
	ds_read_b128 v[114:117], v195 offset:20480
	ds_read_b128 v[118:121], v195 offset:22528
	ds_read_b128 v[140:143], v197 offset:16384
	ds_read_b128 v[144:147], v197 offset:18432
	s_waitcnt lgkmcnt(7)
	s_add_u32 m0, s12, 0xa000
	v_mfma_f32_16x16x32_f16 v[124:127], v[90:93], v[132:135], v[124:127]
	global_load_lds_dwordx4 v190, s[10:11]
	v_mfma_f32_16x16x32_f16 v[44:47], v[94:97], v[132:135], v[44:47]
	v_mfma_f32_16x16x32_f16 v[28:31], v[98:101], v[132:135], v[28:31]
	v_mfma_f32_16x16x32_f16 v[12:15], v[102:105], v[132:135], v[12:15]
	s_waitcnt lgkmcnt(6)
	s_add_u32 m0, s12, 0xb000
	v_mfma_f32_16x16x32_f16 v[56:59], v[90:93], v[136:139], v[56:59]
	global_load_lds_dwordx4 v192, s[10:11]
	v_mfma_f32_16x16x32_f16 v[40:43], v[94:97], v[136:139], v[40:43]
	v_mfma_f32_16x16x32_f16 v[24:27], v[98:101], v[136:139], v[24:27]
	v_mfma_f32_16x16x32_f16 v[8:11], v[102:105], v[136:139], v[8:11]
	s_waitcnt lgkmcnt(1)
	v_mfma_f32_16x16x32_f16 v[124:127], v[106:109], v[140:143], v[124:127]
	v_mfma_f32_16x16x32_f16 v[44:47], v[110:113], v[140:143], v[44:47]
	v_mfma_f32_16x16x32_f16 v[28:31], v[114:117], v[140:143], v[28:31]
	v_mfma_f32_16x16x32_f16 v[12:15], v[118:121], v[140:143], v[12:15]
	s_waitcnt lgkmcnt(0)
	v_mfma_f32_16x16x32_f16 v[56:59], v[106:109], v[144:147], v[56:59]
	v_mfma_f32_16x16x32_f16 v[40:43], v[110:113], v[144:147], v[40:43]
	v_mfma_f32_16x16x32_f16 v[24:27], v[114:117], v[144:147], v[24:27]
	v_mfma_f32_16x16x32_f16 v[8:11], v[118:121], v[144:147], v[8:11]
	s_add_u32 s10, s10, 128
	s_addc_u32 s11, s11, 0
	s_barrier
	ds_read_b128 v[174:177], v196 offset:24576
	ds_read_b128 v[178:181], v196 offset:26624
	ds_read_b128 v[182:185], v197 offset:24576
	ds_read_b128 v[186:189], v197 offset:26624
	s_waitcnt lgkmcnt(3)
	s_add_u32 m0, s12, 0xc000
	v_mfma_f32_16x16x32_f16 v[52:55], v[90:93], v[174:177], v[52:55]
	global_load_lds_dwordx4 v190, s[14:15]
	v_mfma_f32_16x16x32_f16 v[36:39], v[94:97], v[174:177], v[36:39]
	s_add_u32 m0, s12, 0xd000
	v_mfma_f32_16x16x32_f16 v[20:23], v[98:101], v[174:177], v[20:23]
	global_load_lds_dwordx4 v192, s[14:15]
	v_mfma_f32_16x16x32_f16 v[4:7], v[102:105], v[174:177], v[4:7]
	s_waitcnt lgkmcnt(2)
	s_add_u32 m0, s12, 0x4000
	v_mfma_f32_16x16x32_f16 v[48:51], v[90:93], v[178:181], v[48:51]
	global_load_lds_dwordx4 v190, s[8:9]
	v_mfma_f32_16x16x32_f16 v[32:35], v[94:97], v[178:181], v[32:35]
	s_add_u32 m0, s12, 0x5000
	v_mfma_f32_16x16x32_f16 v[16:19], v[98:101], v[178:181], v[16:19]
	global_load_lds_dwordx4 v191, s[8:9]
	v_mfma_f32_16x16x32_f16 v[0:3], v[102:105], v[178:181], v[0:3]
	s_waitcnt lgkmcnt(1)
	s_add_u32 m0, s12, 0x6000
	v_mfma_f32_16x16x32_f16 v[52:55], v[106:109], v[182:185], v[52:55]
	global_load_lds_dwordx4 v192, s[8:9]
	v_mfma_f32_16x16x32_f16 v[36:39], v[110:113], v[182:185], v[36:39]
	v_mfma_f32_16x16x32_f16 v[20:23], v[114:117], v[182:185], v[20:23]
	v_mfma_f32_16x16x32_f16 v[4:7], v[118:121], v[182:185], v[4:7]
	s_waitcnt lgkmcnt(0)
	s_add_u32 m0, s12, 0x7000
	v_mfma_f32_16x16x32_f16 v[48:51], v[106:109], v[186:189], v[48:51]
	global_load_lds_dwordx4 v193, s[8:9]
	v_mfma_f32_16x16x32_f16 v[32:35], v[110:113], v[186:189], v[32:35]
	v_mfma_f32_16x16x32_f16 v[16:19], v[114:117], v[186:189], v[16:19]
	v_mfma_f32_16x16x32_f16 v[0:3], v[118:121], v[186:189], v[0:3]
	s_add_u32 s14, s14, 128
	s_addc_u32 s15, s15, 0
	s_add_u32 s8, s8, 128
	s_addc_u32 s9, s9, 0
	s_waitcnt vmcnt(8)
	s_barrier
	ds_read_b128 v[90:93], v194 offset:0
	ds_read_b128 v[94:97], v194 offset:2048
	ds_read_b128 v[98:101], v194 offset:4096
	ds_read_b128 v[102:105], v194 offset:6144
	ds_read_b128 v[132:135], v196 offset:32768
	ds_read_b128 v[136:139], v196 offset:34816
	ds_read_b128 v[106:109], v195 offset:0
	ds_read_b128 v[110:113], v195 offset:2048
	ds_read_b128 v[114:117], v195 offset:4096
	ds_read_b128 v[118:121], v195 offset:6144
	ds_read_b128 v[140:143], v197 offset:32768
	ds_read_b128 v[144:147], v197 offset:34816
	s_waitcnt lgkmcnt(7)
	s_add_u32 m0, s12, 0xe000
	v_mfma_f32_16x16x32_f16 v[124:127], v[90:93], v[132:135], v[124:127]
	global_load_lds_dwordx4 v190, s[10:11]
	v_mfma_f32_16x16x32_f16 v[44:47], v[94:97], v[132:135], v[44:47]
	v_mfma_f32_16x16x32_f16 v[28:31], v[98:101], v[132:135], v[28:31]
	v_mfma_f32_16x16x32_f16 v[12:15], v[102:105], v[132:135], v[12:15]
	s_waitcnt lgkmcnt(6)
	s_add_u32 m0, s12, 0xf000
	v_mfma_f32_16x16x32_f16 v[56:59], v[90:93], v[136:139], v[56:59]
	global_load_lds_dwordx4 v192, s[10:11]
	v_mfma_f32_16x16x32_f16 v[40:43], v[94:97], v[136:139], v[40:43]
	v_mfma_f32_16x16x32_f16 v[24:27], v[98:101], v[136:139], v[24:27]
	v_mfma_f32_16x16x32_f16 v[8:11], v[102:105], v[136:139], v[8:11]
	s_waitcnt lgkmcnt(1)
	v_mfma_f32_16x16x32_f16 v[124:127], v[106:109], v[140:143], v[124:127]
	v_mfma_f32_16x16x32_f16 v[44:47], v[110:113], v[140:143], v[44:47]
	v_mfma_f32_16x16x32_f16 v[28:31], v[114:117], v[140:143], v[28:31]
	v_mfma_f32_16x16x32_f16 v[12:15], v[118:121], v[140:143], v[12:15]
	s_waitcnt lgkmcnt(0)
	v_mfma_f32_16x16x32_f16 v[56:59], v[106:109], v[144:147], v[56:59]
	v_mfma_f32_16x16x32_f16 v[40:43], v[110:113], v[144:147], v[40:43]
	v_mfma_f32_16x16x32_f16 v[24:27], v[114:117], v[144:147], v[24:27]
	v_mfma_f32_16x16x32_f16 v[8:11], v[118:121], v[144:147], v[8:11]
	s_add_u32 s10, s10, 128
	s_addc_u32 s11, s11, 0
	s_barrier
	ds_read_b128 v[174:177], v196 offset:0
	ds_read_b128 v[178:181], v196 offset:2048
	ds_read_b128 v[182:185], v197 offset:0
	ds_read_b128 v[186:189], v197 offset:2048
	s_waitcnt lgkmcnt(3)
	s_add_u32 m0, s12, 0x10000
	v_mfma_f32_16x16x32_f16 v[52:55], v[90:93], v[174:177], v[52:55]
	global_load_lds_dwordx4 v190, s[14:15]
	v_mfma_f32_16x16x32_f16 v[36:39], v[94:97], v[174:177], v[36:39]
	s_add_u32 m0, s12, 0x11000
	v_mfma_f32_16x16x32_f16 v[20:23], v[98:101], v[174:177], v[20:23]
	global_load_lds_dwordx4 v192, s[14:15]
	v_mfma_f32_16x16x32_f16 v[4:7], v[102:105], v[174:177], v[4:7]
	s_waitcnt lgkmcnt(2)
	s_add_u32 m0, s12, 0x0
	v_mfma_f32_16x16x32_f16 v[48:51], v[90:93], v[178:181], v[48:51]
	global_load_lds_dwordx4 v190, s[8:9]
	v_mfma_f32_16x16x32_f16 v[32:35], v[94:97], v[178:181], v[32:35]
	s_add_u32 m0, s12, 0x1000
	v_mfma_f32_16x16x32_f16 v[16:19], v[98:101], v[178:181], v[16:19]
	global_load_lds_dwordx4 v191, s[8:9]
	v_mfma_f32_16x16x32_f16 v[0:3], v[102:105], v[178:181], v[0:3]
	s_waitcnt lgkmcnt(1)
	s_add_u32 m0, s12, 0x2000
	v_mfma_f32_16x16x32_f16 v[52:55], v[106:109], v[182:185], v[52:55]
	global_load_lds_dwordx4 v192, s[8:9]
	v_mfma_f32_16x16x32_f16 v[36:39], v[110:113], v[182:185], v[36:39]
	v_mfma_f32_16x16x32_f16 v[20:23], v[114:117], v[182:185], v[20:23]
	v_mfma_f32_16x16x32_f16 v[4:7], v[118:121], v[182:185], v[4:7]
	s_waitcnt lgkmcnt(0)
	s_add_u32 m0, s12, 0x3000
	v_mfma_f32_16x16x32_f16 v[48:51], v[106:109], v[186:189], v[48:51]
	global_load_lds_dwordx4 v193, s[8:9]
	v_mfma_f32_16x16x32_f16 v[32:35], v[110:113], v[186:189], v[32:35]
	v_mfma_f32_16x16x32_f16 v[16:19], v[114:117], v[186:189], v[16:19]
	v_mfma_f32_16x16x32_f16 v[0:3], v[118:121], v[186:189], v[0:3]
	s_add_u32 s14, s14, 128
	s_addc_u32 s15, s15, 0
	s_add_u32 s8, s8, 128
	s_addc_u32 s9, s9, 0
	s_waitcnt vmcnt(8)
	s_barrier
	ds_read_b128 v[90:93], v194 offset:16384
	ds_read_b128 v[94:97], v194 offset:18432
	ds_read_b128 v[98:101], v194 offset:20480
	ds_read_b128 v[102:105], v194 offset:22528
	ds_read_b128 v[132:135], v196 offset:8192
	ds_read_b128 v[136:139], v196 offset:10240
	ds_read_b128 v[106:109], v195 offset:16384
	ds_read_b128 v[110:113], v195 offset:18432
	ds_read_b128 v[114:117], v195 offset:20480
	ds_read_b128 v[118:121], v195 offset:22528
	ds_read_b128 v[140:143], v197 offset:8192
	ds_read_b128 v[144:147], v197 offset:10240
	s_waitcnt lgkmcnt(7)
	s_add_u32 m0, s12, 0x8000
	v_mfma_f32_16x16x32_f16 v[124:127], v[90:93], v[132:135], v[124:127]
	global_load_lds_dwordx4 v190, s[10:11]
	v_mfma_f32_16x16x32_f16 v[44:47], v[94:97], v[132:135], v[44:47]
	v_mfma_f32_16x16x32_f16 v[28:31], v[98:101], v[132:135], v[28:31]
	v_mfma_f32_16x16x32_f16 v[12:15], v[102:105], v[132:135], v[12:15]
	s_waitcnt lgkmcnt(6)
	s_add_u32 m0, s12, 0x9000
	v_mfma_f32_16x16x32_f16 v[56:59], v[90:93], v[136:139], v[56:59]
	global_load_lds_dwordx4 v192, s[10:11]
	v_mfma_f32_16x16x32_f16 v[40:43], v[94:97], v[136:139], v[40:43]
	v_mfma_f32_16x16x32_f16 v[24:27], v[98:101], v[136:139], v[24:27]
	v_mfma_f32_16x16x32_f16 v[8:11], v[102:105], v[136:139], v[8:11]
	s_waitcnt lgkmcnt(1)
	v_mfma_f32_16x16x32_f16 v[124:127], v[106:109], v[140:143], v[124:127]
	v_mfma_f32_16x16x32_f16 v[44:47], v[110:113], v[140:143], v[44:47]
	v_mfma_f32_16x16x32_f16 v[28:31], v[114:117], v[140:143], v[28:31]
	v_mfma_f32_16x16x32_f16 v[12:15], v[118:121], v[140:143], v[12:15]
	s_waitcnt lgkmcnt(0)
	v_mfma_f32_16x16x32_f16 v[56:59], v[106:109], v[144:147], v[56:59]
	v_mfma_f32_16x16x32_f16 v[40:43], v[110:113], v[144:147], v[40:43]
	v_mfma_f32_16x16x32_f16 v[24:27], v[114:117], v[144:147], v[24:27]
	v_mfma_f32_16x16x32_f16 v[8:11], v[118:121], v[144:147], v[8:11]
	s_add_u32 s10, s10, 128
	s_addc_u32 s11, s11, 0
	s_barrier
	ds_read_b128 v[174:177], v196 offset:16384
	ds_read_b128 v[178:181], v196 offset:18432
	ds_read_b128 v[182:185], v197 offset:16384
	ds_read_b128 v[186:189], v197 offset:18432
	s_waitcnt lgkmcnt(3)
	s_add_u32 m0, s12, 0xa000
	v_mfma_f32_16x16x32_f16 v[52:55], v[90:93], v[174:177], v[52:55]
	global_load_lds_dwordx4 v190, s[14:15]
	v_mfma_f32_16x16x32_f16 v[36:39], v[94:97], v[174:177], v[36:39]
	s_add_u32 m0, s12, 0xb000
	v_mfma_f32_16x16x32_f16 v[20:23], v[98:101], v[174:177], v[20:23]
	global_load_lds_dwordx4 v192, s[14:15]
	v_mfma_f32_16x16x32_f16 v[4:7], v[102:105], v[174:177], v[4:7]
	s_waitcnt lgkmcnt(2)
	s_add_u32 m0, s12, 0x4000
	v_mfma_f32_16x16x32_f16 v[48:51], v[90:93], v[178:181], v[48:51]
	global_load_lds_dwordx4 v190, s[8:9]
	v_mfma_f32_16x16x32_f16 v[32:35], v[94:97], v[178:181], v[32:35]
	s_add_u32 m0, s12, 0x5000
	v_mfma_f32_16x16x32_f16 v[16:19], v[98:101], v[178:181], v[16:19]
	global_load_lds_dwordx4 v191, s[8:9]
	v_mfma_f32_16x16x32_f16 v[0:3], v[102:105], v[178:181], v[0:3]
	s_waitcnt lgkmcnt(1)
	s_add_u32 m0, s12, 0x6000
	v_mfma_f32_16x16x32_f16 v[52:55], v[106:109], v[182:185], v[52:55]
	global_load_lds_dwordx4 v192, s[8:9]
	v_mfma_f32_16x16x32_f16 v[36:39], v[110:113], v[182:185], v[36:39]
	v_mfma_f32_16x16x32_f16 v[20:23], v[114:117], v[182:185], v[20:23]
	v_mfma_f32_16x16x32_f16 v[4:7], v[118:121], v[182:185], v[4:7]
	s_waitcnt lgkmcnt(0)
	s_add_u32 m0, s12, 0x7000
	v_mfma_f32_16x16x32_f16 v[48:51], v[106:109], v[186:189], v[48:51]
	global_load_lds_dwordx4 v193, s[8:9]
	v_mfma_f32_16x16x32_f16 v[32:35], v[110:113], v[186:189], v[32:35]
	v_mfma_f32_16x16x32_f16 v[16:19], v[114:117], v[186:189], v[16:19]
	v_mfma_f32_16x16x32_f16 v[0:3], v[118:121], v[186:189], v[0:3]
	s_add_u32 s14, s14, 128
	s_addc_u32 s15, s15, 0
	s_add_u32 s8, s8, 128
	s_addc_u32 s9, s9, 0
	s_waitcnt vmcnt(8)
	s_barrier
	ds_read_b128 v[90:93], v194 offset:0
	ds_read_b128 v[94:97], v194 offset:2048
	ds_read_b128 v[98:101], v194 offset:4096
	ds_read_b128 v[102:105], v194 offset:6144
	ds_read_b128 v[132:135], v196 offset:24576
	ds_read_b128 v[136:139], v196 offset:26624
	ds_read_b128 v[106:109], v195 offset:0
	ds_read_b128 v[110:113], v195 offset:2048
	ds_read_b128 v[114:117], v195 offset:4096
	ds_read_b128 v[118:121], v195 offset:6144
	ds_read_b128 v[140:143], v197 offset:24576
	ds_read_b128 v[144:147], v197 offset:26624
	s_waitcnt lgkmcnt(7)
	s_add_u32 m0, s12, 0xc000
	v_mfma_f32_16x16x32_f16 v[124:127], v[90:93], v[132:135], v[124:127]
	global_load_lds_dwordx4 v190, s[10:11]
	v_mfma_f32_16x16x32_f16 v[44:47], v[94:97], v[132:135], v[44:47]
	v_mfma_f32_16x16x32_f16 v[28:31], v[98:101], v[132:135], v[28:31]
	v_mfma_f32_16x16x32_f16 v[12:15], v[102:105], v[132:135], v[12:15]
	s_waitcnt lgkmcnt(6)
	s_add_u32 m0, s12, 0xd000
	v_mfma_f32_16x16x32_f16 v[56:59], v[90:93], v[136:139], v[56:59]
	global_load_lds_dwordx4 v192, s[10:11]
	v_mfma_f32_16x16x32_f16 v[40:43], v[94:97], v[136:139], v[40:43]
	v_mfma_f32_16x16x32_f16 v[24:27], v[98:101], v[136:139], v[24:27]
	v_mfma_f32_16x16x32_f16 v[8:11], v[102:105], v[136:139], v[8:11]
	s_waitcnt lgkmcnt(1)
	v_mfma_f32_16x16x32_f16 v[124:127], v[106:109], v[140:143], v[124:127]
	v_mfma_f32_16x16x32_f16 v[44:47], v[110:113], v[140:143], v[44:47]
	v_mfma_f32_16x16x32_f16 v[28:31], v[114:117], v[140:143], v[28:31]
	v_mfma_f32_16x16x32_f16 v[12:15], v[118:121], v[140:143], v[12:15]
	s_waitcnt lgkmcnt(0)
	v_mfma_f32_16x16x32_f16 v[56:59], v[106:109], v[144:147], v[56:59]
	v_mfma_f32_16x16x32_f16 v[40:43], v[110:113], v[144:147], v[40:43]
	v_mfma_f32_16x16x32_f16 v[24:27], v[114:117], v[144:147], v[24:27]
	v_mfma_f32_16x16x32_f16 v[8:11], v[118:121], v[144:147], v[8:11]
	s_add_u32 s10, s10, 128
	s_addc_u32 s11, s11, 0
	s_barrier
	ds_read_b128 v[174:177], v196 offset:32768
	ds_read_b128 v[178:181], v196 offset:34816
	ds_read_b128 v[182:185], v197 offset:32768
	ds_read_b128 v[186:189], v197 offset:34816
	s_waitcnt lgkmcnt(3)
	s_add_u32 m0, s12, 0xe000
	v_mfma_f32_16x16x32_f16 v[52:55], v[90:93], v[174:177], v[52:55]
	global_load_lds_dwordx4 v190, s[14:15]
	v_mfma_f32_16x16x32_f16 v[36:39], v[94:97], v[174:177], v[36:39]
	s_add_u32 m0, s12, 0xf000
	v_mfma_f32_16x16x32_f16 v[20:23], v[98:101], v[174:177], v[20:23]
	global_load_lds_dwordx4 v192, s[14:15]
	v_mfma_f32_16x16x32_f16 v[4:7], v[102:105], v[174:177], v[4:7]
	s_waitcnt lgkmcnt(2)
	s_add_u32 m0, s12, 0x0
	v_mfma_f32_16x16x32_f16 v[48:51], v[90:93], v[178:181], v[48:51]
	global_load_lds_dwordx4 v190, s[8:9]
	v_mfma_f32_16x16x32_f16 v[32:35], v[94:97], v[178:181], v[32:35]
	s_add_u32 m0, s12, 0x1000
	v_mfma_f32_16x16x32_f16 v[16:19], v[98:101], v[178:181], v[16:19]
	global_load_lds_dwordx4 v191, s[8:9]
	v_mfma_f32_16x16x32_f16 v[0:3], v[102:105], v[178:181], v[0:3]
	s_waitcnt lgkmcnt(1)
	s_add_u32 m0, s12, 0x2000
	v_mfma_f32_16x16x32_f16 v[52:55], v[106:109], v[182:185], v[52:55]
	global_load_lds_dwordx4 v192, s[8:9]
	v_mfma_f32_16x16x32_f16 v[36:39], v[110:113], v[182:185], v[36:39]
	v_mfma_f32_16x16x32_f16 v[20:23], v[114:117], v[182:185], v[20:23]
	v_mfma_f32_16x16x32_f16 v[4:7], v[118:121], v[182:185], v[4:7]
	s_waitcnt lgkmcnt(0)
	s_add_u32 m0, s12, 0x3000
	v_mfma_f32_16x16x32_f16 v[48:51], v[106:109], v[186:189], v[48:51]
	global_load_lds_dwordx4 v193, s[8:9]
	v_mfma_f32_16x16x32_f16 v[32:35], v[110:113], v[186:189], v[32:35]
	v_mfma_f32_16x16x32_f16 v[16:19], v[114:117], v[186:189], v[16:19]
	v_mfma_f32_16x16x32_f16 v[0:3], v[118:121], v[186:189], v[0:3]
	s_add_u32 s14, s14, 128
	s_addc_u32 s15, s15, 0
	s_add_u32 s8, s8, 128
	s_addc_u32 s9, s9, 0
	s_waitcnt vmcnt(8)
	s_barrier
	ds_read_b128 v[90:93], v194 offset:16384
	ds_read_b128 v[94:97], v194 offset:18432
	ds_read_b128 v[98:101], v194 offset:20480
	ds_read_b128 v[102:105], v194 offset:22528
	ds_read_b128 v[132:135], v196 offset:0
	ds_read_b128 v[136:139], v196 offset:2048
	ds_read_b128 v[106:109], v195 offset:16384
	ds_read_b128 v[110:113], v195 offset:18432
	ds_read_b128 v[114:117], v195 offset:20480
	ds_read_b128 v[118:121], v195 offset:22528
	ds_read_b128 v[140:143], v197 offset:0
	ds_read_b128 v[144:147], v197 offset:2048
	s_waitcnt lgkmcnt(7)
	s_add_u32 m0, s12, 0x10000
	v_mfma_f32_16x16x32_f16 v[124:127], v[90:93], v[132:135], v[124:127]
	global_load_lds_dwordx4 v190, s[10:11]
	v_mfma_f32_16x16x32_f16 v[44:47], v[94:97], v[132:135], v[44:47]
	v_mfma_f32_16x16x32_f16 v[28:31], v[98:101], v[132:135], v[28:31]
	v_mfma_f32_16x16x32_f16 v[12:15], v[102:105], v[132:135], v[12:15]
	s_waitcnt lgkmcnt(6)
	s_add_u32 m0, s12, 0x11000
	v_mfma_f32_16x16x32_f16 v[56:59], v[90:93], v[136:139], v[56:59]
	global_load_lds_dwordx4 v192, s[10:11]
	v_mfma_f32_16x16x32_f16 v[40:43], v[94:97], v[136:139], v[40:43]
	v_mfma_f32_16x16x32_f16 v[24:27], v[98:101], v[136:139], v[24:27]
	v_mfma_f32_16x16x32_f16 v[8:11], v[102:105], v[136:139], v[8:11]
	s_waitcnt lgkmcnt(1)
	v_mfma_f32_16x16x32_f16 v[124:127], v[106:109], v[140:143], v[124:127]
	v_mfma_f32_16x16x32_f16 v[44:47], v[110:113], v[140:143], v[44:47]
	v_mfma_f32_16x16x32_f16 v[28:31], v[114:117], v[140:143], v[28:31]
	v_mfma_f32_16x16x32_f16 v[12:15], v[118:121], v[140:143], v[12:15]
	s_waitcnt lgkmcnt(0)
	v_mfma_f32_16x16x32_f16 v[56:59], v[106:109], v[144:147], v[56:59]
	v_mfma_f32_16x16x32_f16 v[40:43], v[110:113], v[144:147], v[40:43]
	v_mfma_f32_16x16x32_f16 v[24:27], v[114:117], v[144:147], v[24:27]
	v_mfma_f32_16x16x32_f16 v[8:11], v[118:121], v[144:147], v[8:11]
	s_add_u32 s10, s10, 128
	s_addc_u32 s11, s11, 0
	s_barrier
	ds_read_b128 v[174:177], v196 offset:8192
	ds_read_b128 v[178:181], v196 offset:10240
	ds_read_b128 v[182:185], v197 offset:8192
	ds_read_b128 v[186:189], v197 offset:10240
	s_waitcnt lgkmcnt(3)
	s_add_u32 m0, s12, 0x8000
	v_mfma_f32_16x16x32_f16 v[52:55], v[90:93], v[174:177], v[52:55]
	global_load_lds_dwordx4 v190, s[14:15]
	v_mfma_f32_16x16x32_f16 v[36:39], v[94:97], v[174:177], v[36:39]
	s_add_u32 m0, s12, 0x9000
	v_mfma_f32_16x16x32_f16 v[20:23], v[98:101], v[174:177], v[20:23]
	global_load_lds_dwordx4 v192, s[14:15]
	v_mfma_f32_16x16x32_f16 v[4:7], v[102:105], v[174:177], v[4:7]
	s_waitcnt lgkmcnt(2)
	s_add_u32 m0, s12, 0x4000
	v_mfma_f32_16x16x32_f16 v[48:51], v[90:93], v[178:181], v[48:51]
	global_load_lds_dwordx4 v190, s[8:9]
	v_mfma_f32_16x16x32_f16 v[32:35], v[94:97], v[178:181], v[32:35]
	s_add_u32 m0, s12, 0x5000
	v_mfma_f32_16x16x32_f16 v[16:19], v[98:101], v[178:181], v[16:19]
	global_load_lds_dwordx4 v191, s[8:9]
	v_mfma_f32_16x16x32_f16 v[0:3], v[102:105], v[178:181], v[0:3]
	s_waitcnt lgkmcnt(1)
	s_add_u32 m0, s12, 0x6000
	v_mfma_f32_16x16x32_f16 v[52:55], v[106:109], v[182:185], v[52:55]
	global_load_lds_dwordx4 v192, s[8:9]
	v_mfma_f32_16x16x32_f16 v[36:39], v[110:113], v[182:185], v[36:39]
	v_mfma_f32_16x16x32_f16 v[20:23], v[114:117], v[182:185], v[20:23]
	v_mfma_f32_16x16x32_f16 v[4:7], v[118:121], v[182:185], v[4:7]
	s_waitcnt lgkmcnt(0)
	s_add_u32 m0, s12, 0x7000
	v_mfma_f32_16x16x32_f16 v[48:51], v[106:109], v[186:189], v[48:51]
	global_load_lds_dwordx4 v193, s[8:9]
	v_mfma_f32_16x16x32_f16 v[32:35], v[110:113], v[186:189], v[32:35]
	v_mfma_f32_16x16x32_f16 v[16:19], v[114:117], v[186:189], v[16:19]
	v_mfma_f32_16x16x32_f16 v[0:3], v[118:121], v[186:189], v[0:3]
	s_add_u32 s14, s14, 128
	s_addc_u32 s15, s15, 0
	s_add_u32 s8, s8, 128
	s_addc_u32 s9, s9, 0
	s_waitcnt vmcnt(8)
	s_barrier
	ds_read_b128 v[90:93], v194 offset:0
	ds_read_b128 v[94:97], v194 offset:2048
	ds_read_b128 v[98:101], v194 offset:4096
	ds_read_b128 v[102:105], v194 offset:6144
	ds_read_b128 v[132:135], v196 offset:16384
	ds_read_b128 v[136:139], v196 offset:18432
	ds_read_b128 v[106:109], v195 offset:0
	ds_read_b128 v[110:113], v195 offset:2048
	ds_read_b128 v[114:117], v195 offset:4096
	ds_read_b128 v[118:121], v195 offset:6144
	ds_read_b128 v[140:143], v197 offset:16384
	ds_read_b128 v[144:147], v197 offset:18432
	s_waitcnt lgkmcnt(7)
	s_add_u32 m0, s12, 0xa000
	v_mfma_f32_16x16x32_f16 v[124:127], v[90:93], v[132:135], v[124:127]
	global_load_lds_dwordx4 v190, s[10:11]
	v_mfma_f32_16x16x32_f16 v[44:47], v[94:97], v[132:135], v[44:47]
	v_mfma_f32_16x16x32_f16 v[28:31], v[98:101], v[132:135], v[28:31]
	v_mfma_f32_16x16x32_f16 v[12:15], v[102:105], v[132:135], v[12:15]
	s_waitcnt lgkmcnt(6)
	s_add_u32 m0, s12, 0xb000
	v_mfma_f32_16x16x32_f16 v[56:59], v[90:93], v[136:139], v[56:59]
	global_load_lds_dwordx4 v192, s[10:11]
	v_mfma_f32_16x16x32_f16 v[40:43], v[94:97], v[136:139], v[40:43]
	v_mfma_f32_16x16x32_f16 v[24:27], v[98:101], v[136:139], v[24:27]
	v_mfma_f32_16x16x32_f16 v[8:11], v[102:105], v[136:139], v[8:11]
	s_waitcnt lgkmcnt(1)
	v_mfma_f32_16x16x32_f16 v[124:127], v[106:109], v[140:143], v[124:127]
	v_mfma_f32_16x16x32_f16 v[44:47], v[110:113], v[140:143], v[44:47]
	v_mfma_f32_16x16x32_f16 v[28:31], v[114:117], v[140:143], v[28:31]
	v_mfma_f32_16x16x32_f16 v[12:15], v[118:121], v[140:143], v[12:15]
	s_waitcnt lgkmcnt(0)
	v_mfma_f32_16x16x32_f16 v[56:59], v[106:109], v[144:147], v[56:59]
	v_mfma_f32_16x16x32_f16 v[40:43], v[110:113], v[144:147], v[40:43]
	v_mfma_f32_16x16x32_f16 v[24:27], v[114:117], v[144:147], v[24:27]
	v_mfma_f32_16x16x32_f16 v[8:11], v[118:121], v[144:147], v[8:11]
	s_add_u32 s10, s10, 128
	s_addc_u32 s11, s11, 0
	s_barrier
	ds_read_b128 v[174:177], v196 offset:24576
	ds_read_b128 v[178:181], v196 offset:26624
	ds_read_b128 v[182:185], v197 offset:24576
	ds_read_b128 v[186:189], v197 offset:26624
	s_waitcnt lgkmcnt(3)
	s_add_u32 m0, s12, 0xc000
	v_mfma_f32_16x16x32_f16 v[52:55], v[90:93], v[174:177], v[52:55]
	global_load_lds_dwordx4 v190, s[14:15]
	v_mfma_f32_16x16x32_f16 v[36:39], v[94:97], v[174:177], v[36:39]
	s_add_u32 m0, s12, 0xd000
	v_mfma_f32_16x16x32_f16 v[20:23], v[98:101], v[174:177], v[20:23]
	global_load_lds_dwordx4 v192, s[14:15]
	v_mfma_f32_16x16x32_f16 v[4:7], v[102:105], v[174:177], v[4:7]
	s_waitcnt lgkmcnt(2)
	s_add_u32 m0, s12, 0x0
	v_mfma_f32_16x16x32_f16 v[48:51], v[90:93], v[178:181], v[48:51]
	global_load_lds_dwordx4 v190, s[8:9]
	v_mfma_f32_16x16x32_f16 v[32:35], v[94:97], v[178:181], v[32:35]
	s_add_u32 m0, s12, 0x1000
	v_mfma_f32_16x16x32_f16 v[16:19], v[98:101], v[178:181], v[16:19]
	global_load_lds_dwordx4 v191, s[8:9]
	v_mfma_f32_16x16x32_f16 v[0:3], v[102:105], v[178:181], v[0:3]
	s_waitcnt lgkmcnt(1)
	s_add_u32 m0, s12, 0x2000
	v_mfma_f32_16x16x32_f16 v[52:55], v[106:109], v[182:185], v[52:55]
	global_load_lds_dwordx4 v192, s[8:9]
	v_mfma_f32_16x16x32_f16 v[36:39], v[110:113], v[182:185], v[36:39]
	v_mfma_f32_16x16x32_f16 v[20:23], v[114:117], v[182:185], v[20:23]
	v_mfma_f32_16x16x32_f16 v[4:7], v[118:121], v[182:185], v[4:7]
	s_waitcnt lgkmcnt(0)
	s_add_u32 m0, s12, 0x3000
	v_mfma_f32_16x16x32_f16 v[48:51], v[106:109], v[186:189], v[48:51]
	global_load_lds_dwordx4 v193, s[8:9]
	v_mfma_f32_16x16x32_f16 v[32:35], v[110:113], v[186:189], v[32:35]
	v_mfma_f32_16x16x32_f16 v[16:19], v[114:117], v[186:189], v[16:19]
	v_mfma_f32_16x16x32_f16 v[0:3], v[118:121], v[186:189], v[0:3]
	s_add_u32 s14, s14, 128
	s_addc_u32 s15, s15, 0
	s_add_u32 s8, s8, 128
	s_addc_u32 s9, s9, 0
	s_waitcnt vmcnt(8)
	s_barrier
	ds_read_b128 v[90:93], v194 offset:16384
	ds_read_b128 v[94:97], v194 offset:18432
	ds_read_b128 v[98:101], v194 offset:20480
	ds_read_b128 v[102:105], v194 offset:22528
	ds_read_b128 v[132:135], v196 offset:32768
	ds_read_b128 v[136:139], v196 offset:34816
	ds_read_b128 v[106:109], v195 offset:16384
	ds_read_b128 v[110:113], v195 offset:18432
	ds_read_b128 v[114:117], v195 offset:20480
	ds_read_b128 v[118:121], v195 offset:22528
	ds_read_b128 v[140:143], v197 offset:32768
	ds_read_b128 v[144:147], v197 offset:34816
	s_waitcnt lgkmcnt(7)
	s_add_u32 m0, s12, 0xe000
	v_mfma_f32_16x16x32_f16 v[124:127], v[90:93], v[132:135], v[124:127]
	global_load_lds_dwordx4 v190, s[10:11]
	v_mfma_f32_16x16x32_f16 v[44:47], v[94:97], v[132:135], v[44:47]
	v_mfma_f32_16x16x32_f16 v[28:31], v[98:101], v[132:135], v[28:31]
	v_mfma_f32_16x16x32_f16 v[12:15], v[102:105], v[132:135], v[12:15]
	s_waitcnt lgkmcnt(6)
	s_add_u32 m0, s12, 0xf000
	v_mfma_f32_16x16x32_f16 v[56:59], v[90:93], v[136:139], v[56:59]
	global_load_lds_dwordx4 v192, s[10:11]
	v_mfma_f32_16x16x32_f16 v[40:43], v[94:97], v[136:139], v[40:43]
	v_mfma_f32_16x16x32_f16 v[24:27], v[98:101], v[136:139], v[24:27]
	v_mfma_f32_16x16x32_f16 v[8:11], v[102:105], v[136:139], v[8:11]
	s_waitcnt lgkmcnt(1)
	v_mfma_f32_16x16x32_f16 v[124:127], v[106:109], v[140:143], v[124:127]
	v_mfma_f32_16x16x32_f16 v[44:47], v[110:113], v[140:143], v[44:47]
	v_mfma_f32_16x16x32_f16 v[28:31], v[114:117], v[140:143], v[28:31]
	v_mfma_f32_16x16x32_f16 v[12:15], v[118:121], v[140:143], v[12:15]
	s_waitcnt lgkmcnt(0)
	v_mfma_f32_16x16x32_f16 v[56:59], v[106:109], v[144:147], v[56:59]
	v_mfma_f32_16x16x32_f16 v[40:43], v[110:113], v[144:147], v[40:43]
	v_mfma_f32_16x16x32_f16 v[24:27], v[114:117], v[144:147], v[24:27]
	v_mfma_f32_16x16x32_f16 v[8:11], v[118:121], v[144:147], v[8:11]
	s_add_u32 s10, s10, 128
	s_addc_u32 s11, s11, 0
	s_barrier
	ds_read_b128 v[174:177], v196 offset:0
	ds_read_b128 v[178:181], v196 offset:2048
	ds_read_b128 v[182:185], v197 offset:0
	ds_read_b128 v[186:189], v197 offset:2048
	s_waitcnt lgkmcnt(3)
	s_add_u32 m0, s12, 0x10000
	v_mfma_f32_16x16x32_f16 v[52:55], v[90:93], v[174:177], v[52:55]
	global_load_lds_dwordx4 v190, s[14:15]
	v_mfma_f32_16x16x32_f16 v[36:39], v[94:97], v[174:177], v[36:39]
	s_add_u32 m0, s12, 0x11000
	v_mfma_f32_16x16x32_f16 v[20:23], v[98:101], v[174:177], v[20:23]
	global_load_lds_dwordx4 v192, s[14:15]
	v_mfma_f32_16x16x32_f16 v[4:7], v[102:105], v[174:177], v[4:7]
	s_waitcnt lgkmcnt(2)
	s_add_u32 m0, s12, 0x4000
	v_mfma_f32_16x16x32_f16 v[48:51], v[90:93], v[178:181], v[48:51]
	global_load_lds_dwordx4 v190, s[8:9]
	v_mfma_f32_16x16x32_f16 v[32:35], v[94:97], v[178:181], v[32:35]
	s_add_u32 m0, s12, 0x5000
	v_mfma_f32_16x16x32_f16 v[16:19], v[98:101], v[178:181], v[16:19]
	global_load_lds_dwordx4 v191, s[8:9]
	v_mfma_f32_16x16x32_f16 v[0:3], v[102:105], v[178:181], v[0:3]
	s_waitcnt lgkmcnt(1)
	s_add_u32 m0, s12, 0x6000
	v_mfma_f32_16x16x32_f16 v[52:55], v[106:109], v[182:185], v[52:55]
	global_load_lds_dwordx4 v192, s[8:9]
	v_mfma_f32_16x16x32_f16 v[36:39], v[110:113], v[182:185], v[36:39]
	v_mfma_f32_16x16x32_f16 v[20:23], v[114:117], v[182:185], v[20:23]
	v_mfma_f32_16x16x32_f16 v[4:7], v[118:121], v[182:185], v[4:7]
	s_waitcnt lgkmcnt(0)
	s_add_u32 m0, s12, 0x7000
	v_mfma_f32_16x16x32_f16 v[48:51], v[106:109], v[186:189], v[48:51]
	global_load_lds_dwordx4 v193, s[8:9]
	v_mfma_f32_16x16x32_f16 v[32:35], v[110:113], v[186:189], v[32:35]
	v_mfma_f32_16x16x32_f16 v[16:19], v[114:117], v[186:189], v[16:19]
	v_mfma_f32_16x16x32_f16 v[0:3], v[118:121], v[186:189], v[0:3]
	s_add_u32 s14, s14, 128
	s_addc_u32 s15, s15, 0
	s_add_u32 s8, s8, 128
	s_addc_u32 s9, s9, 0
	s_waitcnt vmcnt(8)
	s_barrier
	ds_read_b128 v[90:93], v194 offset:0
	ds_read_b128 v[94:97], v194 offset:2048
	ds_read_b128 v[98:101], v194 offset:4096
	ds_read_b128 v[102:105], v194 offset:6144
	ds_read_b128 v[132:135], v196 offset:8192
	ds_read_b128 v[136:139], v196 offset:10240
	ds_read_b128 v[106:109], v195 offset:0
	ds_read_b128 v[110:113], v195 offset:2048
	ds_read_b128 v[114:117], v195 offset:4096
	ds_read_b128 v[118:121], v195 offset:6144
	ds_read_b128 v[140:143], v197 offset:8192
	ds_read_b128 v[144:147], v197 offset:10240
	s_waitcnt lgkmcnt(7)
	s_add_u32 m0, s12, 0x8000
	v_mfma_f32_16x16x32_f16 v[124:127], v[90:93], v[132:135], v[124:127]
	global_load_lds_dwordx4 v190, s[10:11]
	v_mfma_f32_16x16x32_f16 v[44:47], v[94:97], v[132:135], v[44:47]
	v_mfma_f32_16x16x32_f16 v[28:31], v[98:101], v[132:135], v[28:31]
	v_mfma_f32_16x16x32_f16 v[12:15], v[102:105], v[132:135], v[12:15]
	s_waitcnt lgkmcnt(6)
	s_add_u32 m0, s12, 0x9000
	v_mfma_f32_16x16x32_f16 v[56:59], v[90:93], v[136:139], v[56:59]
	global_load_lds_dwordx4 v192, s[10:11]
	v_mfma_f32_16x16x32_f16 v[40:43], v[94:97], v[136:139], v[40:43]
	v_mfma_f32_16x16x32_f16 v[24:27], v[98:101], v[136:139], v[24:27]
	v_mfma_f32_16x16x32_f16 v[8:11], v[102:105], v[136:139], v[8:11]
	s_waitcnt lgkmcnt(1)
	v_mfma_f32_16x16x32_f16 v[124:127], v[106:109], v[140:143], v[124:127]
	v_mfma_f32_16x16x32_f16 v[44:47], v[110:113], v[140:143], v[44:47]
	v_mfma_f32_16x16x32_f16 v[28:31], v[114:117], v[140:143], v[28:31]
	v_mfma_f32_16x16x32_f16 v[12:15], v[118:121], v[140:143], v[12:15]
	s_waitcnt lgkmcnt(0)
	v_mfma_f32_16x16x32_f16 v[56:59], v[106:109], v[144:147], v[56:59]
	v_mfma_f32_16x16x32_f16 v[40:43], v[110:113], v[144:147], v[40:43]
	v_mfma_f32_16x16x32_f16 v[24:27], v[114:117], v[144:147], v[24:27]
	v_mfma_f32_16x16x32_f16 v[8:11], v[118:121], v[144:147], v[8:11]
	s_add_u32 s10, s10, 128
	s_addc_u32 s11, s11, 0
	s_barrier
	ds_read_b128 v[174:177], v196 offset:16384
	ds_read_b128 v[178:181], v196 offset:18432
	ds_read_b128 v[182:185], v197 offset:16384
	ds_read_b128 v[186:189], v197 offset:18432
	s_waitcnt lgkmcnt(3)
	s_add_u32 m0, s12, 0xa000
	v_mfma_f32_16x16x32_f16 v[52:55], v[90:93], v[174:177], v[52:55]
	global_load_lds_dwordx4 v190, s[14:15]
	v_mfma_f32_16x16x32_f16 v[36:39], v[94:97], v[174:177], v[36:39]
	s_add_u32 m0, s12, 0xb000
	v_mfma_f32_16x16x32_f16 v[20:23], v[98:101], v[174:177], v[20:23]
	global_load_lds_dwordx4 v192, s[14:15]
	v_mfma_f32_16x16x32_f16 v[4:7], v[102:105], v[174:177], v[4:7]
	s_waitcnt lgkmcnt(2)
	s_add_u32 m0, s12, 0x0
	v_mfma_f32_16x16x32_f16 v[48:51], v[90:93], v[178:181], v[48:51]
	global_load_lds_dwordx4 v190, s[8:9]
	v_mfma_f32_16x16x32_f16 v[32:35], v[94:97], v[178:181], v[32:35]
	s_add_u32 m0, s12, 0x1000
	v_mfma_f32_16x16x32_f16 v[16:19], v[98:101], v[178:181], v[16:19]
	global_load_lds_dwordx4 v191, s[8:9]
	v_mfma_f32_16x16x32_f16 v[0:3], v[102:105], v[178:181], v[0:3]
	s_waitcnt lgkmcnt(1)
	s_add_u32 m0, s12, 0x2000
	v_mfma_f32_16x16x32_f16 v[52:55], v[106:109], v[182:185], v[52:55]
	global_load_lds_dwordx4 v192, s[8:9]
	v_mfma_f32_16x16x32_f16 v[36:39], v[110:113], v[182:185], v[36:39]
	v_mfma_f32_16x16x32_f16 v[20:23], v[114:117], v[182:185], v[20:23]
	v_mfma_f32_16x16x32_f16 v[4:7], v[118:121], v[182:185], v[4:7]
	s_waitcnt lgkmcnt(0)
	s_add_u32 m0, s12, 0x3000
	v_mfma_f32_16x16x32_f16 v[48:51], v[106:109], v[186:189], v[48:51]
	global_load_lds_dwordx4 v193, s[8:9]
	v_mfma_f32_16x16x32_f16 v[32:35], v[110:113], v[186:189], v[32:35]
	v_mfma_f32_16x16x32_f16 v[16:19], v[114:117], v[186:189], v[16:19]
	v_mfma_f32_16x16x32_f16 v[0:3], v[118:121], v[186:189], v[0:3]
	s_add_u32 s14, s14, 128
	s_addc_u32 s15, s15, 0
	s_add_u32 s8, s8, 128
	s_addc_u32 s9, s9, 0
	s_waitcnt vmcnt(8)
	s_barrier
	ds_read_b128 v[90:93], v194 offset:16384
	ds_read_b128 v[94:97], v194 offset:18432
	ds_read_b128 v[98:101], v194 offset:20480
	ds_read_b128 v[102:105], v194 offset:22528
	ds_read_b128 v[132:135], v196 offset:24576
	ds_read_b128 v[136:139], v196 offset:26624
	ds_read_b128 v[106:109], v195 offset:16384
	ds_read_b128 v[110:113], v195 offset:18432
	ds_read_b128 v[114:117], v195 offset:20480
	ds_read_b128 v[118:121], v195 offset:22528
	ds_read_b128 v[140:143], v197 offset:24576
	ds_read_b128 v[144:147], v197 offset:26624
	s_waitcnt lgkmcnt(7)
	s_add_u32 m0, s12, 0xc000
	v_mfma_f32_16x16x32_f16 v[124:127], v[90:93], v[132:135], v[124:127]
	global_load_lds_dwordx4 v190, s[10:11]
	v_mfma_f32_16x16x32_f16 v[44:47], v[94:97], v[132:135], v[44:47]
	v_mfma_f32_16x16x32_f16 v[28:31], v[98:101], v[132:135], v[28:31]
	v_mfma_f32_16x16x32_f16 v[12:15], v[102:105], v[132:135], v[12:15]
	s_waitcnt lgkmcnt(6)
	s_add_u32 m0, s12, 0xd000
	v_mfma_f32_16x16x32_f16 v[56:59], v[90:93], v[136:139], v[56:59]
	global_load_lds_dwordx4 v192, s[10:11]
	v_mfma_f32_16x16x32_f16 v[40:43], v[94:97], v[136:139], v[40:43]
	v_mfma_f32_16x16x32_f16 v[24:27], v[98:101], v[136:139], v[24:27]
	v_mfma_f32_16x16x32_f16 v[8:11], v[102:105], v[136:139], v[8:11]
	s_waitcnt lgkmcnt(1)
	v_mfma_f32_16x16x32_f16 v[124:127], v[106:109], v[140:143], v[124:127]
	v_mfma_f32_16x16x32_f16 v[44:47], v[110:113], v[140:143], v[44:47]
	v_mfma_f32_16x16x32_f16 v[28:31], v[114:117], v[140:143], v[28:31]
	v_mfma_f32_16x16x32_f16 v[12:15], v[118:121], v[140:143], v[12:15]
	s_waitcnt lgkmcnt(0)
	v_mfma_f32_16x16x32_f16 v[56:59], v[106:109], v[144:147], v[56:59]
	v_mfma_f32_16x16x32_f16 v[40:43], v[110:113], v[144:147], v[40:43]
	v_mfma_f32_16x16x32_f16 v[24:27], v[114:117], v[144:147], v[24:27]
	v_mfma_f32_16x16x32_f16 v[8:11], v[118:121], v[144:147], v[8:11]
	s_add_u32 s10, s10, 128
	s_addc_u32 s11, s11, 0
	s_barrier
	ds_read_b128 v[174:177], v196 offset:32768
	ds_read_b128 v[178:181], v196 offset:34816
	ds_read_b128 v[182:185], v197 offset:32768
	ds_read_b128 v[186:189], v197 offset:34816
	s_waitcnt lgkmcnt(3)
	s_add_u32 m0, s12, 0xe000
	v_mfma_f32_16x16x32_f16 v[52:55], v[90:93], v[174:177], v[52:55]
	global_load_lds_dwordx4 v190, s[14:15]
	v_mfma_f32_16x16x32_f16 v[36:39], v[94:97], v[174:177], v[36:39]
	s_add_u32 m0, s12, 0xf000
	v_mfma_f32_16x16x32_f16 v[20:23], v[98:101], v[174:177], v[20:23]
	global_load_lds_dwordx4 v192, s[14:15]
	v_mfma_f32_16x16x32_f16 v[4:7], v[102:105], v[174:177], v[4:7]
	s_waitcnt lgkmcnt(2)
	s_add_u32 m0, s12, 0x4000
	v_mfma_f32_16x16x32_f16 v[48:51], v[90:93], v[178:181], v[48:51]
	global_load_lds_dwordx4 v190, s[8:9]
	v_mfma_f32_16x16x32_f16 v[32:35], v[94:97], v[178:181], v[32:35]
	s_add_u32 m0, s12, 0x5000
	v_mfma_f32_16x16x32_f16 v[16:19], v[98:101], v[178:181], v[16:19]
	global_load_lds_dwordx4 v191, s[8:9]
	v_mfma_f32_16x16x32_f16 v[0:3], v[102:105], v[178:181], v[0:3]
	s_waitcnt lgkmcnt(1)
	s_add_u32 m0, s12, 0x6000
	v_mfma_f32_16x16x32_f16 v[52:55], v[106:109], v[182:185], v[52:55]
	global_load_lds_dwordx4 v192, s[8:9]
	v_mfma_f32_16x16x32_f16 v[36:39], v[110:113], v[182:185], v[36:39]
	v_mfma_f32_16x16x32_f16 v[20:23], v[114:117], v[182:185], v[20:23]
	v_mfma_f32_16x16x32_f16 v[4:7], v[118:121], v[182:185], v[4:7]
	s_waitcnt lgkmcnt(0)
	s_add_u32 m0, s12, 0x7000
	v_mfma_f32_16x16x32_f16 v[48:51], v[106:109], v[186:189], v[48:51]
	global_load_lds_dwordx4 v193, s[8:9]
	v_mfma_f32_16x16x32_f16 v[32:35], v[110:113], v[186:189], v[32:35]
	v_mfma_f32_16x16x32_f16 v[16:19], v[114:117], v[186:189], v[16:19]
	v_mfma_f32_16x16x32_f16 v[0:3], v[118:121], v[186:189], v[0:3]
	s_add_u32 s14, s14, 128
	s_addc_u32 s15, s15, 0
	s_add_u32 s8, s8, 128
	s_addc_u32 s9, s9, 0
	s_add_i32 s13, s13, 1
	s_cmp_lt_u32 s13, 3
	s_cbranch_scc1 .Lgout_loop
	global_load_dwordx4 v[60:63], v148, s[38:39] offset:0
	global_load_dwordx4 v[64:67], v148, s[38:39] offset:64
	global_load_dwordx4 v[68:71], v148, s[38:39] offset:128
	global_load_dwordx4 v[72:75], v148, s[38:39] offset:192
	global_load_dwordx4 v[76:79], v150, s[36:37] offset:0
	global_load_dwordx4 v[80:83], v150, s[36:37] offset:64
	global_load_dwordx4 v[84:87], v150, s[36:37] offset:128
	global_load_dwordx4 v[200:203], v150, s[36:37] offset:192
	global_load_dwordx4 v[204:207], v151, s[36:37] offset:0
	global_load_dwordx4 v[210:213], v151, s[36:37] offset:64
	global_load_dwordx4 v[222:225], v151, s[36:37] offset:128
	global_load_dwordx4 v[226:229], v151, s[36:37] offset:192
	global_load_dwordx4 v[230:233], v152, s[36:37] offset:0
	global_load_dwordx4 v[234:237], v152, s[36:37] offset:64
	global_load_dwordx4 v[238:241], v152, s[36:37] offset:128
	global_load_dwordx4 v[242:245], v152, s[36:37] offset:192
	global_load_dwordx4 v[246:249], v153, s[36:37] offset:0
	global_load_dwordx4 v[158:161], v153, s[36:37] offset:64
	global_load_dwordx4 v[162:165], v153, s[36:37] offset:128
	global_load_dwordx4 v[154:157], v153, s[36:37] offset:192
	s_waitcnt vmcnt(28)
	s_barrier
	ds_read_b128 v[90:93], v194 offset:0
	ds_read_b128 v[94:97], v194 offset:2048
	ds_read_b128 v[98:101], v194 offset:4096
	ds_read_b128 v[102:105], v194 offset:6144
	ds_read_b128 v[132:135], v196 offset:0
	ds_read_b128 v[136:139], v196 offset:2048
	ds_read_b128 v[106:109], v195 offset:0
	ds_read_b128 v[110:113], v195 offset:2048
	ds_read_b128 v[114:117], v195 offset:4096
	ds_read_b128 v[118:121], v195 offset:6144
	ds_read_b128 v[140:143], v197 offset:0
	ds_read_b128 v[144:147], v197 offset:2048
	s_waitcnt lgkmcnt(7)
	v_mfma_f32_16x16x32_f16 v[124:127], v[90:93], v[132:135], v[124:127]
	v_mfma_f32_16x16x32_f16 v[44:47], v[94:97], v[132:135], v[44:47]
	v_mfma_f32_16x16x32_f16 v[28:31], v[98:101], v[132:135], v[28:31]
	v_mfma_f32_16x16x32_f16 v[12:15], v[102:105], v[132:135], v[12:15]
	s_waitcnt lgkmcnt(6)
	v_mfma_f32_16x16x32_f16 v[56:59], v[90:93], v[136:139], v[56:59]
	v_mfma_f32_16x16x32_f16 v[40:43], v[94:97], v[136:139], v[40:43]
	v_mfma_f32_16x16x32_f16 v[24:27], v[98:101], v[136:139], v[24:27]
	v_mfma_f32_16x16x32_f16 v[8:11], v[102:105], v[136:139], v[8:11]
	s_waitcnt lgkmcnt(1)
	v_mfma_f32_16x16x32_f16 v[124:127], v[106:109], v[140:143], v[124:127]
	v_mfma_f32_16x16x32_f16 v[44:47], v[110:113], v[140:143], v[44:47]
	v_mfma_f32_16x16x32_f16 v[28:31], v[114:117], v[140:143], v[28:31]
	v_mfma_f32_16x16x32_f16 v[12:15], v[118:121], v[140:143], v[12:15]
	s_waitcnt lgkmcnt(0)
	v_mfma_f32_16x16x32_f16 v[56:59], v[106:109], v[144:147], v[56:59]
	v_mfma_f32_16x16x32_f16 v[40:43], v[110:113], v[144:147], v[40:43]
	v_mfma_f32_16x16x32_f16 v[24:27], v[114:117], v[144:147], v[24:27]
	v_mfma_f32_16x16x32_f16 v[8:11], v[118:121], v[144:147], v[8:11]
	s_barrier
	ds_read_b128 v[174:177], v196 offset:8192
	ds_read_b128 v[178:181], v196 offset:10240
	ds_read_b128 v[182:185], v197 offset:8192
	ds_read_b128 v[186:189], v197 offset:10240
	s_waitcnt lgkmcnt(3)
	v_mfma_f32_16x16x32_f16 v[52:55], v[90:93], v[174:177], v[52:55]
	v_mfma_f32_16x16x32_f16 v[36:39], v[94:97], v[174:177], v[36:39]
	v_mfma_f32_16x16x32_f16 v[20:23], v[98:101], v[174:177], v[20:23]
	v_mfma_f32_16x16x32_f16 v[4:7], v[102:105], v[174:177], v[4:7]
	s_waitcnt lgkmcnt(2)
	v_mfma_f32_16x16x32_f16 v[48:51], v[90:93], v[178:181], v[48:51]
	v_mfma_f32_16x16x32_f16 v[32:35], v[94:97], v[178:181], v[32:35]
	v_mfma_f32_16x16x32_f16 v[16:19], v[98:101], v[178:181], v[16:19]
	v_mfma_f32_16x16x32_f16 v[0:3], v[102:105], v[178:181], v[0:3]
	s_waitcnt lgkmcnt(1)
	v_mfma_f32_16x16x32_f16 v[52:55], v[106:109], v[182:185], v[52:55]
	v_mfma_f32_16x16x32_f16 v[36:39], v[110:113], v[182:185], v[36:39]
	v_mfma_f32_16x16x32_f16 v[20:23], v[114:117], v[182:185], v[20:23]
	v_mfma_f32_16x16x32_f16 v[4:7], v[118:121], v[182:185], v[4:7]
	s_waitcnt lgkmcnt(0)
	v_mfma_f32_16x16x32_f16 v[48:51], v[106:109], v[186:189], v[48:51]
	v_mfma_f32_16x16x32_f16 v[32:35], v[110:113], v[186:189], v[32:35]
	v_mfma_f32_16x16x32_f16 v[16:19], v[114:117], v[186:189], v[16:19]
	v_mfma_f32_16x16x32_f16 v[0:3], v[118:121], v[186:189], v[0:3]
	s_waitcnt vmcnt(20)
	s_barrier
	ds_read_b128 v[90:93], v194 offset:16384
	ds_read_b128 v[94:97], v194 offset:18432
	ds_read_b128 v[98:101], v194 offset:20480
	ds_read_b128 v[102:105], v194 offset:22528
	ds_read_b128 v[132:135], v196 offset:16384
	ds_read_b128 v[136:139], v196 offset:18432
	ds_read_b128 v[106:109], v195 offset:16384
	ds_read_b128 v[110:113], v195 offset:18432
	ds_read_b128 v[114:117], v195 offset:20480
	ds_read_b128 v[118:121], v195 offset:22528
	ds_read_b128 v[140:143], v197 offset:16384
	ds_read_b128 v[144:147], v197 offset:18432
	s_waitcnt lgkmcnt(7)
	v_mfma_f32_16x16x32_f16 v[124:127], v[90:93], v[132:135], v[124:127]
	v_mfma_f32_16x16x32_f16 v[44:47], v[94:97], v[132:135], v[44:47]
	v_mfma_f32_16x16x32_f16 v[28:31], v[98:101], v[132:135], v[28:31]
	v_mfma_f32_16x16x32_f16 v[12:15], v[102:105], v[132:135], v[12:15]
	s_waitcnt lgkmcnt(6)
	v_mfma_f32_16x16x32_f16 v[56:59], v[90:93], v[136:139], v[56:59]
	v_mfma_f32_16x16x32_f16 v[40:43], v[94:97], v[136:139], v[40:43]
	v_mfma_f32_16x16x32_f16 v[24:27], v[98:101], v[136:139], v[24:27]
	v_mfma_f32_16x16x32_f16 v[8:11], v[102:105], v[136:139], v[8:11]
	s_waitcnt lgkmcnt(1)
	v_mfma_f32_16x16x32_f16 v[124:127], v[106:109], v[140:143], v[124:127]
	v_mfma_f32_16x16x32_f16 v[44:47], v[110:113], v[140:143], v[44:47]
	v_mfma_f32_16x16x32_f16 v[28:31], v[114:117], v[140:143], v[28:31]
	v_mfma_f32_16x16x32_f16 v[12:15], v[118:121], v[140:143], v[12:15]
	s_waitcnt lgkmcnt(0)
	v_mfma_f32_16x16x32_f16 v[56:59], v[106:109], v[144:147], v[56:59]
	v_mfma_f32_16x16x32_f16 v[40:43], v[110:113], v[144:147], v[40:43]
	v_mfma_f32_16x16x32_f16 v[24:27], v[114:117], v[144:147], v[24:27]
	v_mfma_f32_16x16x32_f16 v[8:11], v[118:121], v[144:147], v[8:11]
	s_barrier
	ds_read_b128 v[174:177], v196 offset:24576
	ds_read_b128 v[178:181], v196 offset:26624
	ds_read_b128 v[182:185], v197 offset:24576
	ds_read_b128 v[186:189], v197 offset:26624
	s_waitcnt lgkmcnt(3)
	v_mfma_f32_16x16x32_f16 v[52:55], v[90:93], v[174:177], v[52:55]
	v_mfma_f32_16x16x32_f16 v[36:39], v[94:97], v[174:177], v[36:39]
	v_mfma_f32_16x16x32_f16 v[20:23], v[98:101], v[174:177], v[20:23]
	v_mfma_f32_16x16x32_f16 v[4:7], v[102:105], v[174:177], v[4:7]
	s_waitcnt lgkmcnt(2)
	v_mfma_f32_16x16x32_f16 v[48:51], v[90:93], v[178:181], v[48:51]
	v_mfma_f32_16x16x32_f16 v[32:35], v[94:97], v[178:181], v[32:35]
	v_mfma_f32_16x16x32_f16 v[16:19], v[98:101], v[178:181], v[16:19]
	v_mfma_f32_16x16x32_f16 v[0:3], v[102:105], v[178:181], v[0:3]
	s_waitcnt lgkmcnt(1)
	v_mfma_f32_16x16x32_f16 v[52:55], v[106:109], v[182:185], v[52:55]
	v_mfma_f32_16x16x32_f16 v[36:39], v[110:113], v[182:185], v[36:39]
	v_mfma_f32_16x16x32_f16 v[20:23], v[114:117], v[182:185], v[20:23]
	v_mfma_f32_16x16x32_f16 v[4:7], v[118:121], v[182:185], v[4:7]
	s_waitcnt lgkmcnt(0)
	v_mfma_f32_16x16x32_f16 v[48:51], v[106:109], v[186:189], v[48:51]
	v_mfma_f32_16x16x32_f16 v[32:35], v[110:113], v[186:189], v[32:35]
	v_mfma_f32_16x16x32_f16 v[16:19], v[114:117], v[186:189], v[16:19]
	v_mfma_f32_16x16x32_f16 v[0:3], v[118:121], v[186:189], v[0:3]
	s_nop 7
	s_waitcnt vmcnt(0)
	v_pk_mul_f32 v[124:125], v[124:125], v[60:61]
	v_pk_mul_f32 v[126:127], v[126:127], v[62:63]
	v_pk_fma_f32 v[124:125], v[76:77], s[96:97], v[124:125] op_sel_hi:[1,0,1]
	v_pk_fma_f32 v[126:127], v[78:79], s[96:97], v[126:127] op_sel_hi:[1,0,1]
	global_store_dwordx4 v150, v[124:127], s[18:19] offset:0
	v_pk_mul_f32 v[44:45], v[44:45], v[64:65]
	v_pk_mul_f32 v[46:47], v[46:47], v[66:67]
	v_pk_fma_f32 v[44:45], v[80:81], s[96:97], v[44:45] op_sel_hi:[1,0,1]
	v_pk_fma_f32 v[46:47], v[82:83], s[96:97], v[46:47] op_sel_hi:[1,0,1]
	global_store_dwordx4 v150, v[44:47], s[18:19] offset:64
	v_pk_mul_f32 v[28:29], v[28:29], v[68:69]
	v_pk_mul_f32 v[30:31], v[30:31], v[70:71]
	v_pk_fma_f32 v[28:29], v[84:85], s[96:97], v[28:29] op_sel_hi:[1,0,1]
	v_pk_fma_f32 v[30:31], v[86:87], s[96:97], v[30:31] op_sel_hi:[1,0,1]
	global_store_dwordx4 v150, v[28:31], s[18:19] offset:128
	v_pk_mul_f32 v[12:13], v[12:13], v[72:73]
	v_pk_mul_f32 v[14:15], v[14:15], v[74:75]
	v_pk_fma_f32 v[12:13], v[200:201], s[96:97], v[12:13] op_sel_hi:[1,0,1]
	v_pk_fma_f32 v[14:15], v[202:203], s[96:97], v[14:15] op_sel_hi:[1,0,1]
	global_store_dwordx4 v150, v[12:15], s[18:19] offset:192
	v_pk_mul_f32 v[56:57], v[56:57], v[60:61]
	v_pk_mul_f32 v[58:59], v[58:59], v[62:63]
	v_pk_fma_f32 v[56:57], v[204:205], s[96:97], v[56:57] op_sel_hi:[1,0,1]
	v_pk_fma_f32 v[58:59], v[206:207], s[96:97], v[58:59] op_sel_hi:[1,0,1]
	global_store_dwordx4 v151, v[56:59], s[18:19] offset:0
	v_pk_mul_f32 v[40:41], v[40:41], v[64:65]
	v_pk_mul_f32 v[42:43], v[42:43], v[66:67]
	v_pk_fma_f32 v[40:41], v[210:211], s[96:97], v[40:41] op_sel_hi:[1,0,1]
	v_pk_fma_f32 v[42:43], v[212:213], s[96:97], v[42:43] op_sel_hi:[1,0,1]
	global_store_dwordx4 v151, v[40:43], s[18:19] offset:64
	v_pk_mul_f32 v[24:25], v[24:25], v[68:69]
	v_pk_mul_f32 v[26:27], v[26:27], v[70:71]
	v_pk_fma_f32 v[24:25], v[222:223], s[96:97], v[24:25] op_sel_hi:[1,0,1]
	v_pk_fma_f32 v[26:27], v[224:225], s[96:97], v[26:27] op_sel_hi:[1,0,1]
	global_store_dwordx4 v151, v[24:27], s[18:19] offset:128
	v_pk_mul_f32 v[8:9], v[8:9], v[72:73]
	v_pk_mul_f32 v[10:11], v[10:11], v[74:75]
	v_pk_fma_f32 v[8:9], v[226:227], s[96:97], v[8:9] op_sel_hi:[1,0,1]
	v_pk_fma_f32 v[10:11], v[228:229], s[96:97], v[10:11] op_sel_hi:[1,0,1]
	global_store_dwordx4 v151, v[8:11], s[18:19] offset:192
	v_pk_mul_f32 v[52:53], v[52:53], v[60:61]
	v_pk_mul_f32 v[54:55], v[54:55], v[62:63]
	v_pk_fma_f32 v[52:53], v[230:231], s[96:97], v[52:53] op_sel_hi:[1,0,1]
	v_pk_fma_f32 v[54:55], v[232:233], s[96:97], v[54:55] op_sel_hi:[1,0,1]
	global_store_dwordx4 v152, v[52:55], s[18:19] offset:0
	v_pk_mul_f32 v[36:37], v[36:37], v[64:65]
	v_pk_mul_f32 v[38:39], v[38:39], v[66:67]
	v_pk_fma_f32 v[36:37], v[234:235], s[96:97], v[36:37] op_sel_hi:[1,0,1]
	v_pk_fma_f32 v[38:39], v[236:237], s[96:97], v[38:39] op_sel_hi:[1,0,1]
	global_store_dwordx4 v152, v[36:39], s[18:19] offset:64
	v_pk_mul_f32 v[20:21], v[20:21], v[68:69]
	v_pk_mul_f32 v[22:23], v[22:23], v[70:71]
	v_pk_fma_f32 v[20:21], v[238:239], s[96:97], v[20:21] op_sel_hi:[1,0,1]
	v_pk_fma_f32 v[22:23], v[240:241], s[96:97], v[22:23] op_sel_hi:[1,0,1]
	global_store_dwordx4 v152, v[20:23], s[18:19] offset:128
	v_pk_mul_f32 v[4:5], v[4:5], v[72:73]
	v_pk_mul_f32 v[6:7], v[6:7], v[74:75]
	v_pk_fma_f32 v[4:5], v[242:243], s[96:97], v[4:5] op_sel_hi:[1,0,1]
	v_pk_fma_f32 v[6:7], v[244:245], s[96:97], v[6:7] op_sel_hi:[1,0,1]
	global_store_dwordx4 v152, v[4:7], s[18:19] offset:192
	v_pk_mul_f32 v[48:49], v[48:49], v[60:61]
	v_pk_mul_f32 v[50:51], v[50:51], v[62:63]
	v_pk_fma_f32 v[48:49], v[246:247], s[96:97], v[48:49] op_sel_hi:[1,0,1]
	v_pk_fma_f32 v[50:51], v[248:249], s[96:97], v[50:51] op_sel_hi:[1,0,1]
	global_store_dwordx4 v153, v[48:51], s[18:19] offset:0
	v_pk_mul_f32 v[32:33], v[32:33], v[64:65]
	v_pk_mul_f32 v[34:35], v[34:35], v[66:67]
	v_pk_fma_f32 v[32:33], v[158:159], s[96:97], v[32:33] op_sel_hi:[1,0,1]
	v_pk_fma_f32 v[34:35], v[160:161], s[96:97], v[34:35] op_sel_hi:[1,0,1]
	global_store_dwordx4 v153, v[32:35], s[18:19] offset:64
	v_pk_mul_f32 v[16:17], v[16:17], v[68:69]
	v_pk_mul_f32 v[18:19], v[18:19], v[70:71]
	v_pk_fma_f32 v[16:17], v[162:163], s[96:97], v[16:17] op_sel_hi:[1,0,1]
	v_pk_fma_f32 v[18:19], v[164:165], s[96:97], v[18:19] op_sel_hi:[1,0,1]
	global_store_dwordx4 v153, v[16:19], s[18:19] offset:128
	v_pk_mul_f32 v[0:1], v[0:1], v[72:73]
	v_pk_mul_f32 v[2:3], v[2:3], v[74:75]
	v_pk_fma_f32 v[0:1], v[154:155], s[96:97], v[0:1] op_sel_hi:[1,0,1]
	v_pk_fma_f32 v[2:3], v[156:157], s[96:97], v[2:3] op_sel_hi:[1,0,1]
	global_store_dwordx4 v153, v[0:3], s[18:19] offset:192
	s_add_i32 s6, s6, 1
	s_lshl_b32 s0, s6, 3
	v_readlane_b32 s4, v254, 36
	s_or_b32 s0, s0, s4
	v_readlane_b32 s4, v254, 37
	s_mul_i32 s0, s0, s4
	v_readlane_b32 s4, v254, 38
	s_add_i32 s0, s0, s4
	s_cmpk_gt_u32 s0, 0x5ff
	s_cbranch_scc1 .LBB0_1481
	s_branch .LBB0_1352
